# mixer work queue: retention items interleaved with attention items instead of all before/after
# speedup vs baseline: 1.0091x; 1.0001x over previous
.LBB0_312:
	s_or_b64 exec, exec, s[0:1]
	s_add_i32 s0, 0, 0x20000
	v_readlane_b32 s6, v253, 7
	s_cmp_lg_u32 s0, -1
	v_readlane_b32 s7, v253, 8
	s_cselect_b32 s0, s0, 0
	s_cselect_b32 s1, s7, 0
	s_waitcnt vmcnt(0)
	v_mov_b32_e32 v2, s0
	v_mov_b32_e32 v3, s1
	s_waitcnt lgkmcnt(0)
	s_barrier
	flat_load_dword v0, v[2:3] sc0 sc1
	s_waitcnt vmcnt(0)
	s_mov_b64 s[0:1], -1
	s_waitcnt lgkmcnt(0)
	s_barrier
	v_readfirstlane_b32 s76, v0
	s_cmp_ge_i32 s76, s75
	s_cbranch_scc1 .LBB0_307
	s_cmp_lt_u32 s76, 128
	s_cbranch_scc0 .Lq_seg2
	s_lshr_b32 s100, s76, 1
	s_bitcmp1_b32 s76, 0
	s_cselect_b32 s101, 96, 0
	s_add_i32 s76, s100, s101
	s_branch .Lq_done
.Lq_seg2:
	s_cmp_lt_u32 s76, 160
	s_cbranch_scc0 .Lq_seg3
	s_sub_i32 s76, s76, 64
	s_branch .Lq_done
.Lq_seg3:
	s_sub_i32 s100, s76, 160
	s_cmp_lt_u32 s100, 136
	s_cbranch_scc0 .Lq_tail
	s_lshr_b32 s101, s100, 1
	s_bitcmp1_b32 s100, 0
	s_cbranch_scc1 .Lq_retc
	s_add_i32 s76, s101, 160
	s_branch .Lq_done
.Lq_retc:
	s_add_i32 s76, s101, 232
	s_add_i32 s76, s76, s97
	s_branch .Lq_done
.Lq_tail:
	s_sub_i32 s76, s76, 68
.Lq_done:
	s_cmp_gt_i32 s76, 63
	s_cbranch_scc0 .LBB0_631
	s_cmpk_gt_u32 s76, 0x5f
	s_cbranch_scc0 .LBB0_609
	v_readlane_b32 s0, v255, 22
	s_cmp_ge_u32 s76, s0
	s_mov_b64 s[0:1], -1
	s_cbranch_scc0 .LBB0_360
	s_sub_i32 s14, s76, s97
	s_add_i32 s14, s14, 0xff18
	s_sext_i32_i16 s0, s14
	s_mulk_i32 s0, 0x7879
	s_lshr_b32 s1, s0, 31
	s_ashr_i32 s38, s0, 19
	s_add_i32 s38, s38, s1
	s_lshl_b32 s0, s38, 3
	v_readlane_b32 s1, v254, 52
	s_or_b32 s6, s0, s1
	s_mov_b64 s[0:1], exec
	v_readlane_b32 s8, v253, 0
	v_readlane_b32 s9, v253, 1
	s_and_b64 s[8:9], s[0:1], s[8:9]
	s_mov_b64 exec, s[8:9]
	s_cbranch_execz .LBB0_331
	s_ashr_i32 s7, s6, 31
	s_lshl_b64 s[8:9], s[6:7], 2
	v_readlane_b32 s7, v255, 20
	s_add_u32 s8, s7, s8
	v_readlane_b32 s7, v255, 21
	s_addc_u32 s9, s7, s9
	s_mov_b32 s7, 0x1000000
	s_branch .LBB0_320
